# fox steady-state loop: prefill (decay-table) reads issued before both per-tile barriers on the loop-back path
# baseline (speedup 1.0000x reference)
.Lfx_head2:
	s_waitcnt lgkmcnt(4)
	v_sub_f32_e32 v97, v81, v242
	v_sub_f32_e32 v96, v80, v242
	v_sub_f32_e32 v95, v79, v242
	v_sub_f32_e32 v94, v78, v242
	v_sub_f32_e32 v93, v77, v242
	v_sub_f32_e32 v92, v76, v242
	v_sub_f32_e32 v91, v75, v242
	v_sub_f32_e32 v90, v74, v242
	v_sub_f32_e32 v89, v73, v242
	v_sub_f32_e32 v88, v72, v242
	v_sub_f32_e32 v87, v71, v242
	v_sub_f32_e32 v86, v70, v242
	v_sub_f32_e32 v85, v69, v242
	v_sub_f32_e32 v84, v68, v242
	v_sub_f32_e32 v83, v67, v242
	v_sub_f32_e32 v82, v66, v242
	s_waitcnt lgkmcnt(0)
	v_sub_f32_e32 v81, v251, v242
	v_sub_f32_e32 v80, v250, v242
	v_sub_f32_e32 v79, v249, v242
	v_sub_f32_e32 v78, v248, v242
	v_sub_f32_e32 v77, v247, v242
	v_sub_f32_e32 v76, v246, v242
	v_sub_f32_e32 v75, v245, v242
	v_sub_f32_e32 v74, v244, v242
	v_sub_f32_e32 v73, v171, v242
	v_sub_f32_e32 v72, v170, v242
	v_sub_f32_e32 v71, v169, v242
	v_sub_f32_e32 v70, v168, v242
	v_sub_f32_e32 v69, v165, v242
	v_sub_f32_e32 v68, v164, v242
	v_sub_f32_e32 v67, v163, v242
	v_sub_f32_e32 v66, v162, v242
	v_add_u32_e32 v167, s35, v194
	ds_read_b64_tr_b16 v[162:163], v167 offset:24576
	ds_read_b64_tr_b16 v[164:165], v167 offset:25088
	v_add_f32_e32 v110, v50, v51
	v_add_f32_e32 v110, v52, v110
	v_add_f32_e32 v110, v53, v110
	v_add_f32_e32 v110, v54, v110
	v_add_f32_e32 v110, v55, v110
	v_cvt_pk_bf16_f32 v126, v50, v51
	v_cvt_pk_bf16_f32 v127, v52, v53
	v_mfma_f32_32x32x16_bf16 v[82:97], v[158:161], v[114:117], v[82:97]
	ds_read_b64_tr_b16 v[50:51], v167 offset:28672
	ds_read_b64_tr_b16 v[52:53], v167 offset:29184
	v_add_f32_e32 v110, v56, v110
	v_add_f32_e32 v110, v57, v110
	v_add_f32_e32 v110, v58, v110
	v_add_f32_e32 v110, v59, v110
	v_cvt_pk_bf16_f32 v128, v54, v55
	v_cvt_pk_bf16_f32 v129, v56, v57
	v_mfma_f32_32x32x16_bf16 v[66:81], v[154:157], v[114:117], v[66:81]
	ds_read_b64_tr_b16 v[54:55], v167 offset:25600
	ds_read_b64_tr_b16 v[56:57], v167 offset:26112
	v_add_f32_e32 v110, v60, v110
	v_add_f32_e32 v110, v61, v110
	v_add_f32_e32 v110, v62, v110
	v_add_f32_e32 v110, v63, v110
	v_cvt_pk_bf16_f32 v122, v58, v59
	v_cvt_pk_bf16_f32 v123, v60, v61
	v_mfma_f32_32x32x16_bf16 v[82:97], v[150:153], v[106:109], v[82:97]
	ds_read_b64_tr_b16 v[58:59], v167 offset:29696
	ds_read_b64_tr_b16 v[60:61], v167 offset:30208
	v_add_f32_e32 v110, v64, v110
	v_add_f32_e32 v110, v65, v110
	v_add_f32_e32 v110, v34, v110
	v_add_f32_e32 v110, v35, v110
	v_cvt_pk_bf16_f32 v124, v62, v63
	v_cvt_pk_bf16_f32 v125, v64, v65
	v_mfma_f32_32x32x16_bf16 v[66:81], v[146:149], v[106:109], v[66:81]
	ds_read_b64_tr_b16 v[62:63], v167 offset:26624
	ds_read_b64_tr_b16 v[64:65], v167 offset:27136
	v_add_f32_e32 v110, v36, v110
	v_add_f32_e32 v110, v37, v110
	v_add_f32_e32 v110, v38, v110
	v_add_f32_e32 v110, v39, v110
	v_cvt_pk_bf16_f32 v118, v34, v35
	v_cvt_pk_bf16_f32 v119, v36, v37
	v_mfma_f32_32x32x16_bf16 v[82:97], v[142:145], v[102:105], v[82:97]
	ds_read_b64_tr_b16 v[34:35], v167 offset:30720
	ds_read_b64_tr_b16 v[36:37], v167 offset:31232
	v_add_f32_e32 v110, v40, v110
	v_add_f32_e32 v110, v41, v110
	v_add_f32_e32 v110, v42, v110
	v_add_f32_e32 v110, v43, v110
	v_cvt_pk_bf16_f32 v120, v38, v39
	v_cvt_pk_bf16_f32 v121, v40, v41
	v_mfma_f32_32x32x16_bf16 v[66:81], v[138:141], v[102:105], v[66:81]
	ds_read_b64_tr_b16 v[38:39], v167 offset:27648
	ds_read_b64_tr_b16 v[40:41], v167 offset:28160
	v_add_f32_e32 v110, v44, v110
	v_add_f32_e32 v110, v45, v110
	v_add_f32_e32 v110, v46, v110
	v_mfma_f32_32x32x16_bf16 v[82:97], v[134:137], v[98:101], v[82:97]
	v_add_f32_e32 v134, v47, v110
	v_cvt_pk_bf16_f32 v110, v42, v43
	v_cvt_pk_bf16_f32 v111, v44, v45
	ds_read_b64_tr_b16 v[42:43], v167 offset:31744
	ds_read_b64_tr_b16 v[44:45], v167 offset:32256
	v_add_f32_e32 v112, v48, v134
	v_add_f32_e32 v112, v49, v112
	v_mfma_f32_32x32x16_bf16 v[66:81], v[130:133], v[98:101], v[66:81]
	v_add_f32_e32 v130, 0, v112
	v_cvt_pk_bf16_f32 v112, v46, v47
	v_cvt_pk_bf16_f32 v113, v48, v49
	s_add_u32 s36, s12, 0xfffa0000
	s_addc_u32 s37, s13, -1
	s_add_i32 s27, s27, s84
	s_mov_b32 s35, m0
	s_mov_b32 m0, s27
	s_nop 0
	global_load_lds_dwordx4 v191, s[36:37]
	s_mov_b32 m0, s35
	s_add_u32 s36, s10, 0xfffa0000
	s_addc_u32 s37, s11, -1
	s_add_i32 s27, s28, s85
	s_mov_b32 s35, m0
	s_mov_b32 m0, s27
	s_nop 0
	global_load_lds_dwordx4 v192, s[36:37]
	s_mov_b32 m0, s35
	v_add_f32_e32 v167, v243, v130
	s_waitcnt lgkmcnt(14)
	v_mfma_f32_32x32x16_bf16 v[2:17], v[126:129], v[162:165], v[2:17]
	v_exp_f32_e32 v82, v82
	v_exp_f32_e32 v83, v83
	v_exp_f32_e32 v84, v84
	v_exp_f32_e32 v85, v85
	s_waitcnt lgkmcnt(12)
	v_mfma_f32_32x32x16_bf16 v[18:33], v[126:129], v[50:53], v[18:33]
	v_exp_f32_e32 v86, v86
	v_exp_f32_e32 v87, v87
	v_exp_f32_e32 v88, v88
	v_exp_f32_e32 v89, v89
	v_add_u32_e32 v46, s28, v193
	ds_read_b128 v[162:165], v46
	ds_read_b128 v[154:157], v46 offset:512
	s_waitcnt lgkmcnt(12)
	v_mfma_f32_32x32x16_bf16 v[2:17], v[122:125], v[54:57], v[2:17]
	v_exp_f32_e32 v90, v90
	v_exp_f32_e32 v91, v91
	v_exp_f32_e32 v92, v92
	v_exp_f32_e32 v93, v93
	ds_read_b128 v[150:153], v46 offset:2048
	ds_read_b128 v[146:149], v46 offset:2560
	s_waitcnt lgkmcnt(12)
	v_mfma_f32_32x32x16_bf16 v[18:33], v[122:125], v[58:61], v[18:33]
	v_exp_f32_e32 v94, v94
	v_exp_f32_e32 v95, v95
	v_exp_f32_e32 v96, v96
	v_exp_f32_e32 v97, v97
	ds_read_b128 v[142:145], v46 offset:4096
	ds_read_b128 v[138:141], v46 offset:4608
	s_waitcnt lgkmcnt(12)
	v_mfma_f32_32x32x16_bf16 v[2:17], v[118:121], v[62:65], v[2:17]
	v_exp_f32_e32 v66, v66
	v_exp_f32_e32 v67, v67
	v_exp_f32_e32 v68, v68
	v_exp_f32_e32 v69, v69
	ds_read_b128 v[134:137], v46 offset:6144
	ds_read_b128 v[130:133], v46 offset:6656
	s_waitcnt lgkmcnt(12)
	v_mfma_f32_32x32x16_bf16 v[18:33], v[118:121], v[34:37], v[18:33]
	v_exp_f32_e32 v70, v70
	v_exp_f32_e32 v71, v71
	v_exp_f32_e32 v72, v72
	v_exp_f32_e32 v73, v73
	s_waitcnt lgkmcnt(10)
	v_mfma_f32_32x32x16_bf16 v[2:17], v[110:113], v[38:41], v[2:17]
	v_exp_f32_e32 v74, v74
	v_exp_f32_e32 v75, v75
	v_exp_f32_e32 v76, v76
	v_exp_f32_e32 v77, v77
	s_waitcnt lgkmcnt(8)
	v_mfma_f32_32x32x16_bf16 v[18:33], v[110:113], v[42:45], v[18:33]
	v_exp_f32_e32 v78, v78
	v_exp_f32_e32 v79, v79
	v_exp_f32_e32 v80, v80
	v_exp_f32_e32 v81, v81
	ds_read_b128 v[34:37], v166 offset:256
	ds_read_b128 v[38:41], v166 offset:288
	ds_read_b128 v[42:45], v166 offset:320
	ds_read_b128 v[46:49], v166 offset:352
	ds_read_b128 v[158:161], v166 offset:384
	ds_read_b128 v[168:171], v166 offset:416
	ds_read_b128 v[244:247], v166 offset:448
	ds_read_b128 v[248:251], v166 offset:480
	s_waitcnt vmcnt(2) lgkmcnt(8)
	s_barrier
	s_add_i32 s27, s28, 0x2000
	s_cmpk_lg_i32 s28, 0x4000
	s_cselect_b32 s27, s27, 0
	s_waitcnt lgkmcnt(4)
	v_sub_f32_e32 v65, v49, v242
	v_sub_f32_e32 v64, v48, v242
	v_sub_f32_e32 v63, v47, v242
	v_sub_f32_e32 v62, v46, v242
	v_sub_f32_e32 v61, v45, v242
	v_sub_f32_e32 v60, v44, v242
	v_sub_f32_e32 v59, v43, v242
	v_sub_f32_e32 v58, v42, v242
	v_sub_f32_e32 v57, v41, v242
	v_sub_f32_e32 v56, v40, v242
	v_sub_f32_e32 v55, v39, v242
	v_sub_f32_e32 v54, v38, v242
	v_sub_f32_e32 v53, v37, v242
	v_sub_f32_e32 v52, v36, v242
	v_sub_f32_e32 v51, v35, v242
	v_sub_f32_e32 v50, v34, v242
	s_waitcnt lgkmcnt(0)
	v_sub_f32_e32 v49, v251, v242
	v_sub_f32_e32 v48, v250, v242
	v_sub_f32_e32 v47, v249, v242
	v_sub_f32_e32 v46, v248, v242
	v_sub_f32_e32 v45, v247, v242
	v_sub_f32_e32 v44, v246, v242
	v_sub_f32_e32 v43, v245, v242
	v_sub_f32_e32 v42, v244, v242
	v_sub_f32_e32 v41, v171, v242
	v_sub_f32_e32 v40, v170, v242
	v_sub_f32_e32 v39, v169, v242
	v_sub_f32_e32 v38, v168, v242
	v_sub_f32_e32 v37, v161, v242
	v_sub_f32_e32 v36, v160, v242
	v_sub_f32_e32 v35, v159, v242
	v_sub_f32_e32 v34, v158, v242
	v_add_u32_e32 v172, s34, v194
	ds_read_b64_tr_b16 v[158:159], v172 offset:24576
	ds_read_b64_tr_b16 v[160:161], v172 offset:25088
	v_mfma_f32_32x32x16_bf16 v[50:65], v[162:165], v[114:117], v[50:65]
	v_add_f32_e32 v110, v82, v83
	v_add_f32_e32 v110, v84, v110
	v_add_f32_e32 v110, v85, v110
	v_add_f32_e32 v110, v86, v110
	v_add_f32_e32 v110, v87, v110
	v_cvt_pk_bf16_f32 v126, v82, v83
	v_cvt_pk_bf16_f32 v127, v84, v85
	ds_read_b64_tr_b16 v[82:83], v172 offset:28672
	ds_read_b64_tr_b16 v[84:85], v172 offset:29184
	v_mfma_f32_32x32x16_bf16 v[34:49], v[154:157], v[114:117], v[34:49]
	v_add_f32_e32 v110, v88, v110
	v_add_f32_e32 v110, v89, v110
	v_add_f32_e32 v110, v90, v110
	v_add_f32_e32 v110, v91, v110
	v_cvt_pk_bf16_f32 v128, v86, v87
	v_cvt_pk_bf16_f32 v129, v88, v89
	ds_read_b64_tr_b16 v[86:87], v172 offset:25600
	ds_read_b64_tr_b16 v[88:89], v172 offset:26112
	v_mfma_f32_32x32x16_bf16 v[50:65], v[150:153], v[106:109], v[50:65]
	v_add_f32_e32 v110, v92, v110
	v_add_f32_e32 v110, v93, v110
	v_add_f32_e32 v110, v94, v110
	v_add_f32_e32 v110, v95, v110
	v_cvt_pk_bf16_f32 v122, v90, v91
	v_cvt_pk_bf16_f32 v123, v92, v93
	ds_read_b64_tr_b16 v[90:91], v172 offset:29696
	ds_read_b64_tr_b16 v[92:93], v172 offset:30208
	v_mfma_f32_32x32x16_bf16 v[34:49], v[146:149], v[106:109], v[34:49]
	v_add_f32_e32 v110, v96, v110
	v_add_f32_e32 v110, v97, v110
	v_add_f32_e32 v110, v66, v110
	v_add_f32_e32 v110, v67, v110
	v_cvt_pk_bf16_f32 v124, v94, v95
	v_cvt_pk_bf16_f32 v125, v96, v97
	ds_read_b64_tr_b16 v[94:95], v172 offset:26624
	ds_read_b64_tr_b16 v[96:97], v172 offset:27136
	v_mfma_f32_32x32x16_bf16 v[50:65], v[142:145], v[102:105], v[50:65]
	v_add_f32_e32 v110, v68, v110
	v_add_f32_e32 v110, v69, v110
	v_add_f32_e32 v110, v70, v110
	v_add_f32_e32 v110, v71, v110
	v_cvt_pk_bf16_f32 v118, v66, v67
	v_cvt_pk_bf16_f32 v119, v68, v69
	ds_read_b64_tr_b16 v[66:67], v172 offset:30720
	ds_read_b64_tr_b16 v[68:69], v172 offset:31232
	v_mfma_f32_32x32x16_bf16 v[34:49], v[138:141], v[102:105], v[34:49]
	v_add_f32_e32 v110, v72, v110
	v_add_f32_e32 v110, v73, v110
	v_add_f32_e32 v110, v74, v110
	v_add_f32_e32 v110, v75, v110
	v_cvt_pk_bf16_f32 v120, v70, v71
	v_cvt_pk_bf16_f32 v121, v72, v73
	ds_read_b64_tr_b16 v[70:71], v172 offset:27648
	ds_read_b64_tr_b16 v[72:73], v172 offset:28160
	v_mfma_f32_32x32x16_bf16 v[50:65], v[134:137], v[98:101], v[50:65]
	v_add_f32_e32 v110, v76, v110
	v_add_f32_e32 v110, v77, v110
	v_add_f32_e32 v110, v78, v110
	v_add_f32_e32 v134, v79, v110
	v_cvt_pk_bf16_f32 v110, v74, v75
	v_cvt_pk_bf16_f32 v111, v76, v77
	ds_read_b64_tr_b16 v[74:75], v172 offset:31744
	ds_read_b64_tr_b16 v[76:77], v172 offset:32256
	v_mfma_f32_32x32x16_bf16 v[34:49], v[130:133], v[98:101], v[34:49]
	v_add_f32_e32 v112, v80, v134
	v_add_f32_e32 v112, v81, v112
	v_add_f32_e32 v130, 0, v112
	v_cvt_pk_bf16_f32 v112, v78, v79
	v_cvt_pk_bf16_f32 v113, v80, v81
	s_add_i32 s34, s28, s84
	s_mov_b32 s35, m0
	s_mov_b32 m0, s34
	s_nop 0
	global_load_lds_dwordx4 v191, s[12:13]
	s_mov_b32 m0, s35
	s_add_i32 s34, s27, s85
	s_mov_b32 s35, m0
	s_mov_b32 m0, s34
	s_nop 0
	global_load_lds_dwordx4 v192, s[10:11]
	s_mov_b32 m0, s35
	v_add_f32_e32 v243, v167, v130
	s_add_i32 s31, s31, 2
	s_waitcnt lgkmcnt(14)
	v_mfma_f32_32x32x16_bf16 v[2:17], v[126:129], v[158:161], v[2:17]
	v_exp_f32_e32 v50, v50
	v_exp_f32_e32 v51, v51
	v_exp_f32_e32 v52, v52
	v_exp_f32_e32 v53, v53
	s_waitcnt lgkmcnt(12)
	v_mfma_f32_32x32x16_bf16 v[18:33], v[126:129], v[82:85], v[18:33]
	v_exp_f32_e32 v54, v54
	v_exp_f32_e32 v55, v55
	v_exp_f32_e32 v56, v56
	v_exp_f32_e32 v57, v57
	v_add_u32_e32 v78, s27, v193
	ds_read_b128 v[158:161], v78
	ds_read_b128 v[154:157], v78 offset:512
	s_waitcnt lgkmcnt(12)
	v_mfma_f32_32x32x16_bf16 v[2:17], v[122:125], v[86:89], v[2:17]
	v_exp_f32_e32 v58, v58
	v_exp_f32_e32 v59, v59
	v_exp_f32_e32 v60, v60
	v_exp_f32_e32 v61, v61
	ds_read_b128 v[150:153], v78 offset:2048
	ds_read_b128 v[146:149], v78 offset:2560
	s_waitcnt lgkmcnt(12)
	v_mfma_f32_32x32x16_bf16 v[18:33], v[122:125], v[90:93], v[18:33]
	v_exp_f32_e32 v62, v62
	v_exp_f32_e32 v63, v63
	v_exp_f32_e32 v64, v64
	v_exp_f32_e32 v65, v65
	ds_read_b128 v[142:145], v78 offset:4096
	ds_read_b128 v[138:141], v78 offset:4608
	s_waitcnt lgkmcnt(12)
	v_mfma_f32_32x32x16_bf16 v[2:17], v[118:121], v[94:97], v[2:17]
	v_exp_f32_e32 v34, v34
	v_exp_f32_e32 v35, v35
	v_exp_f32_e32 v36, v36
	v_exp_f32_e32 v37, v37
	ds_read_b128 v[134:137], v78 offset:6144
	ds_read_b128 v[130:133], v78 offset:6656
	s_waitcnt lgkmcnt(12)
	v_mfma_f32_32x32x16_bf16 v[18:33], v[118:121], v[66:69], v[18:33]
	v_exp_f32_e32 v38, v38
	v_exp_f32_e32 v39, v39
	v_exp_f32_e32 v40, v40
	v_exp_f32_e32 v41, v41
	s_waitcnt lgkmcnt(10)
	v_mfma_f32_32x32x16_bf16 v[2:17], v[110:113], v[70:73], v[2:17]
	v_exp_f32_e32 v42, v42
	v_exp_f32_e32 v43, v43
	v_exp_f32_e32 v44, v44
	v_exp_f32_e32 v45, v45
	s_waitcnt lgkmcnt(8)
	v_mfma_f32_32x32x16_bf16 v[18:33], v[110:113], v[74:77], v[18:33]
	v_exp_f32_e32 v46, v46
	v_exp_f32_e32 v47, v47
	v_exp_f32_e32 v48, v48
	v_exp_f32_e32 v49, v49
	s_add_i32 s34, s27, 0x2000
	s_cmpk_lg_i32 s27, 0x4000
	s_cselect_b32 s34, s34, 0
	s_add_u32 s10, s10, 0xc0000
	s_addc_u32 s11, s11, 0
	s_cmp_ge_i32 s31, s30
	s_cbranch_scc1 .Lfx_exit
	ds_read_b128 v[66:69], v166 offset:512
	ds_read_b128 v[70:73], v166 offset:544
	ds_read_b128 v[74:77], v166 offset:576
	ds_read_b128 v[78:81], v166 offset:608
	ds_read_b128 v[162:165], v166 offset:640
	ds_read_b128 v[168:171], v166 offset:672
	ds_read_b128 v[244:247], v166 offset:704
	ds_read_b128 v[248:251], v166 offset:736
	s_waitcnt vmcnt(2) lgkmcnt(8)
	s_barrier
	s_add_u32 s12, s12, 0xc0000
	s_addc_u32 s13, s13, 0
	v_add_u32_e32 v166, 0x200, v166
	s_mov_b32 s35, s28
	s_mov_b32 s28, s34
	s_mov_b32 s34, s27
	s_branch .Lfx_head2
.Lfx_exit:
	s_waitcnt vmcnt(2) lgkmcnt(0)
	s_barrier
	s_add_u32 s12, s12, 0xc0000
	s_addc_u32 s13, s13, 0
	v_add_u32_e32 v166, 0x200, v166
	s_mov_b32 s35, s28
	v_readlane_b32 s30, v253, 58
	s_add_i32 s10, s31, 1
	s_cmp_ge_i32 s10, s25
	s_cbranch_scc0 .LBB0_676
